# attention merge epilogue: the 31 partner-partial LDS reads issued together after the hand-off instead of one LDS round trip per output element
# speedup vs baseline: 1.0026x; 1.0026x over previous
; __device__ __forceinline__ unsigned cvt_pk_bf16(float lo, float hi) { unsigned r; asm volatile("v_cvt_pk_bf16_f32 %0, %1, %2" : "=v"(r) : "v"(lo), "v"(hi)); return r; }
; __device__ __forceinline__ void attn_item(const Ptrs& P, unsigned char* lds, int b, int tq0, int tid) {
;     ...
;         if (lane == 0) xa[48 + w] = aseq;
;         while (xa[48 + (w ^ 1)] != aseq) { }
;         const float* pc = (const float*)(stg + (w ^ 1) * 32 * SP);
;         float wa[4], wb[4];
; #pragma unroll
;         for (int j = 0; j < 4; ++j) { const float mo = pc[2048 + j * 64 + lane], lo = pc[2304 + j * 64 + lane];
;             const float mm = fmaxf(mrun[j], mo); const float ea = __expf(mrun[j] - mm), eb = __expf(mo - mm);
;             const float inv = 1.f / (lrun[j] * ea + lo * eb); wa[j] = ea * inv; wb[j] = eb * inv; }
;         bf16_t* op = P.QL + (rowb + tq) * 4096;
; #pragma unroll
;         for (int dt = 0; dt < 8; ++dt)
; #pragma unroll
;             for (int j = 0; j < 4; ++j) { const float v = (half ? oacc[8 + dt][j] : oacc[dt][j]) * wa[j] + pc[(dt * 4 + j) * 64 + lane] * wb[j];
;                 op[(4 * g + j) * 256 + 16 * (8 * half + dt) + r16] = (bf16_t)(cvt_pk_bf16(v, 0.f) & 0xffffu); }
.LBB0_931:
	v_mov_b64_e32 v[0:1], s[20:21]
	ds_read_b32 v0, v0
	s_waitcnt lgkmcnt(0)
	v_cmp_eq_u32_e32 vcc, v0, v218
	s_or_b64 s[14:15], vcc, s[14:15]
	s_andn2_b64 exec, exec, s[14:15]
	s_cbranch_execnz .LBB0_931
	s_or_b64 exec, exec, s[14:15]
	s_mulk_i32 s16, 0x4200
	v_add_u32_e32 v8, s16, v203
	ds_read_b32 v52, v8 offset:256
	ds_read_b32 v53, v8 offset:512
	ds_read_b32 v54, v8 offset:768
	ds_read_b32 v55, v8 offset:1024
	ds_read_b32 v56, v8 offset:1280
	ds_read_b32 v57, v8 offset:1536
	ds_read_b32 v58, v8 offset:1792
	ds_read_b32 v59, v8 offset:2048
	ds_read_b32 v60, v8 offset:2304
	ds_read_b32 v61, v8 offset:2560
	ds_read_b32 v62, v8 offset:2816
	ds_read_b32 v63, v8 offset:3072
	ds_read_b32 v64, v8 offset:3328
	ds_read_b32 v65, v8 offset:3584
	ds_read_b32 v66, v8 offset:3840
	ds_read_b32 v67, v8 offset:4096
	ds_read_b32 v72, v8 offset:4352
	ds_read_b32 v73, v8 offset:4608
	ds_read_b32 v74, v8 offset:4864
	ds_read_b32 v75, v8 offset:5120
	ds_read_b32 v76, v8 offset:5376
	ds_read_b32 v77, v8 offset:5632
	ds_read_b32 v78, v8 offset:5888
	ds_read_b32 v79, v8 offset:6144
	ds_read_b32 v128, v8 offset:6400
	ds_read_b32 v129, v8 offset:6656
	ds_read_b32 v130, v8 offset:6912
	ds_read_b32 v131, v8 offset:7168
	ds_read_b32 v152, v8 offset:7424
	ds_read_b32 v153, v8 offset:7680
	ds_read_b32 v154, v8 offset:7936
	s_nop 0
	ds_read2st64_b32 v[0:1], v8 offset1:32
	v_max_f32_e32 v4, v164, v164
	ds_read2st64_b32 v[2:3], v8 offset0:35 offset1:36
	v_cndmask_b32_e64 v17, v149, v109, s[12:13]
	s_waitcnt lgkmcnt(1)
	v_max_f32_e32 v5, v1, v1
	v_max_f32_e32 v4, v4, v5
	v_sub_f32_e32 v1, v1, v4
	v_sub_f32_e32 v5, v164, v4
	v_mul_f32_e32 v1, 0x3fb8aa3b, v1
	v_mul_f32_e32 v4, 0x3fb8aa3b, v5
	v_exp_f32_e32 v1, v1
	v_exp_f32_e32 v9, v4
	ds_read2st64_b32 v[4:5], v8 offset0:37 offset1:38
	ds_read_b32 v10, v8 offset:9984
	ds_read2st64_b32 v[6:7], v8 offset0:33 offset1:34
	s_waitcnt lgkmcnt(3)
	v_mul_f32_e32 v3, v3, v1
	v_fmac_f32_e32 v3, v191, v9
	v_div_scale_f32 v11, s[14:15], v3, v3, 1.0
	v_rcp_f32_e32 v12, v11
	s_nop 0
	v_fma_f32 v13, -v11, v12, 1.0
	v_fmac_f32_e32 v12, v13, v12
	v_div_scale_f32 v13, vcc, 1.0, v3, 1.0
	v_mul_f32_e32 v14, v13, v12
	v_fma_f32 v15, -v11, v14, v13
	v_fmac_f32_e32 v14, v15, v12
	v_fma_f32 v11, -v11, v14, v13
	s_waitcnt lgkmcnt(0)
	v_max_f32_e32 v13, v6, v6
	v_max_f32_e32 v15, v233, v233
	v_max_f32_e32 v13, v15, v13
	v_sub_f32_e32 v6, v6, v13
	v_sub_f32_e32 v15, v233, v13
	v_mul_f32_e32 v6, 0x3fb8aa3b, v6
	v_mul_f32_e32 v15, 0x3fb8aa3b, v15
	v_exp_f32_e32 v6, v6
	v_exp_f32_e32 v13, v15
	v_div_fmas_f32 v11, v11, v12, v14
	v_div_fixup_f32 v3, v11, v3, 1.0
	v_mul_f32_e32 v4, v4, v6
	v_fmac_f32_e32 v4, v190, v13
	v_div_scale_f32 v12, s[14:15], v4, v4, 1.0
	v_rcp_f32_e32 v14, v12
	v_mul_f32_e32 v9, v9, v3
	v_mul_f32_e32 v3, v1, v3
	v_mul_f32_e32 v0, v0, v3
	v_fma_f32 v1, -v12, v14, 1.0
	v_fmac_f32_e32 v14, v1, v14
	v_div_scale_f32 v1, vcc, 1.0, v4, 1.0
	v_mul_f32_e32 v11, v1, v14
	v_fma_f32 v15, -v12, v11, v1
	v_fmac_f32_e32 v11, v15, v14
	v_fma_f32 v1, -v12, v11, v1
	v_max_f32_e32 v12, v7, v7
	v_max_f32_e32 v15, v234, v234
	v_max_f32_e32 v12, v15, v12
	v_sub_f32_e32 v7, v7, v12
	v_sub_f32_e32 v15, v234, v12
	v_mul_f32_e32 v7, 0x3fb8aa3b, v7
	v_mul_f32_e32 v15, 0x3fb8aa3b, v15
	v_exp_f32_e32 v7, v7
	v_exp_f32_e32 v12, v15
	v_div_fmas_f32 v1, v1, v14, v11
	v_div_fixup_f32 v1, v1, v4, 1.0
	v_mul_f32_e32 v5, v5, v7
	v_fmac_f32_e32 v5, v187, v12
	v_div_scale_f32 v11, s[14:15], v5, v5, 1.0
	v_rcp_f32_e32 v14, v11
	v_mul_f32_e32 v4, v13, v1
	v_mul_f32_e32 v6, v6, v1
	v_fma_f32 v1, -v11, v14, 1.0
	v_fmac_f32_e32 v14, v1, v14
	v_div_scale_f32 v1, vcc, 1.0, v5, 1.0
	v_mul_f32_e32 v13, v1, v14
	v_fma_f32 v15, -v11, v13, v1
	v_fmac_f32_e32 v13, v15, v14
	v_fma_f32 v1, -v11, v13, v1
	v_max_f32_e32 v11, v2, v2
	v_max_f32_e32 v15, v235, v235
	v_max_f32_e32 v11, v15, v11
	v_sub_f32_e32 v2, v2, v11
	v_sub_f32_e32 v15, v235, v11
	v_mul_f32_e32 v2, 0x3fb8aa3b, v2
	v_mul_f32_e32 v15, 0x3fb8aa3b, v15
	v_exp_f32_e32 v2, v2
	v_exp_f32_e32 v11, v15
	v_div_fmas_f32 v1, v1, v14, v13
	v_div_fixup_f32 v1, v1, v5, 1.0
	v_mul_f32_e32 v10, v10, v2
	v_fmac_f32_e32 v10, v186, v11
	v_div_scale_f32 v13, s[14:15], v10, v10, 1.0
	v_rcp_f32_e32 v14, v13
	v_mul_f32_e32 v5, v12, v1
	v_mul_f32_e32 v7, v7, v1
	v_fma_f32 v1, -v13, v14, 1.0
	v_fmac_f32_e32 v14, v1, v14
	v_div_scale_f32 v1, vcc, 1.0, v10, 1.0
	v_mul_f32_e32 v12, v1, v14
	v_fma_f32 v15, -v13, v12, v1
	v_fmac_f32_e32 v12, v15, v14
	v_cndmask_b32_e64 v15, v148, v108, s[12:13]
	v_fmac_f32_e32 v0, v15, v9
	v_cvt_pk_bf16_f32 v15, v0, v165
	s_nop 0
	v_fma_f32 v13, -v13, v12, v1
	v_or_b32_e32 v1, v181, v204
	v_lshlrev_b32_e32 v164, 1, v1
	v_lshl_add_u64 v[0:1], v[184:185], 0, v[164:165]
	global_store_short v[0:1], v15, off
	s_waitcnt lgkmcnt(0)
	v_mul_f32_e32 v15, v6, v52
	v_fmac_f32_e32 v15, v17, v4
	v_cvt_pk_bf16_f32 v15, v15, v165
	s_nop 0
	v_div_fmas_f32 v12, v13, v14, v12
	v_div_fixup_f32 v10, v12, v10, 1.0
	v_cndmask_b32_e64 v12, v150, v110, s[12:13]
	global_store_short v[0:1], v15, off offset:512
	s_waitcnt lgkmcnt(0)
	v_mul_f32_e32 v13, v7, v53
	v_fmac_f32_e32 v13, v12, v5
	v_cvt_pk_bf16_f32 v12, v13, v165
	s_nop 0
	v_mul_f32_e32 v2, v2, v10
	v_mul_f32_e32 v11, v11, v10
	v_cndmask_b32_e64 v10, v151, v111, s[12:13]
	global_store_short v[0:1], v12, off offset:1024
	s_waitcnt lgkmcnt(0)
	v_mul_f32_e32 v12, v2, v54
	v_fmac_f32_e32 v12, v10, v11
	v_cvt_pk_bf16_f32 v10, v12, v165
	s_nop 0
	global_store_short v[0:1], v10, off offset:1536
	v_cndmask_b32_e64 v10, v136, v100, s[12:13]
	v_cndmask_b32_e64 v13, v137, v101, s[12:13]
	s_waitcnt lgkmcnt(0)
; __device__ __forceinline__ unsigned cvt_pk_bf16(float lo, float hi) { unsigned r; asm volatile("v_cvt_pk_bf16_f32 %0, %1, %2" : "=v"(r) : "v"(lo), "v"(hi)); return r; }
; __device__ __forceinline__ void attn_item(const Ptrs& P, unsigned char* lds, int b, int tq0, int tid) {
;     ...
;         bf16_t* op = P.QL + (rowb + tq) * 4096;
; #pragma unroll
;         for (int dt = 0; dt < 8; ++dt)
; #pragma unroll
;             for (int j = 0; j < 4; ++j) { const float v = (half ? oacc[8 + dt][j] : oacc[dt][j]) * wa[j] + pc[(dt * 4 + j) * 64 + lane] * wb[j];
;                 op[(4 * g + j) * 256 + 16 * (8 * half + dt) + r16] = (bf16_t)(cvt_pk_bf16(v, 0.f) & 0xffffu); }
	v_mul_f32_e32 v12, v3, v55
	v_fmac_f32_e32 v12, v10, v9
	v_cvt_pk_bf16_f32 v10, v12, v165
	s_nop 0
	global_store_short v[0:1], v10, off offset:32
	s_waitcnt lgkmcnt(0)
	v_mul_f32_e32 v10, v6, v56
	v_fmac_f32_e32 v10, v13, v4
	v_cvt_pk_bf16_f32 v10, v10, v165
	s_nop 0
	v_cndmask_b32_e64 v13, v138, v102, s[12:13]
	global_store_short v[0:1], v10, off offset:544
	s_waitcnt lgkmcnt(0)
	v_mul_f32_e32 v10, v7, v57
	v_fmac_f32_e32 v10, v13, v5
	v_cvt_pk_bf16_f32 v10, v10, v165
	s_nop 0
	v_cndmask_b32_e64 v13, v139, v103, s[12:13]
	global_store_short v[0:1], v10, off offset:1056
	s_waitcnt lgkmcnt(0)
	v_mul_f32_e32 v10, v2, v58
	v_fmac_f32_e32 v10, v13, v11
	v_cvt_pk_bf16_f32 v10, v10, v165
	s_nop 0
	global_store_short v[0:1], v10, off offset:1568
	v_cndmask_b32_e64 v10, v124, v84, s[12:13]
	v_cndmask_b32_e64 v13, v125, v85, s[12:13]
	s_waitcnt lgkmcnt(0)
	v_mul_f32_e32 v12, v3, v59
	v_fmac_f32_e32 v12, v10, v9
	v_cvt_pk_bf16_f32 v10, v12, v165
	s_nop 0
	global_store_short v[0:1], v10, off offset:64
	s_waitcnt lgkmcnt(0)
	v_mul_f32_e32 v10, v6, v60
	v_fmac_f32_e32 v10, v13, v4
	v_cvt_pk_bf16_f32 v10, v10, v165
	s_nop 0
	v_cndmask_b32_e64 v13, v126, v86, s[12:13]
	global_store_short v[0:1], v10, off offset:576
	s_waitcnt lgkmcnt(0)
	v_mul_f32_e32 v10, v7, v61
	v_fmac_f32_e32 v10, v13, v5
	v_cvt_pk_bf16_f32 v10, v10, v165
	s_nop 0
	v_cndmask_b32_e64 v13, v127, v87, s[12:13]
	global_store_short v[0:1], v10, off offset:1088
	s_waitcnt lgkmcnt(0)
	v_mul_f32_e32 v10, v2, v62
	v_fmac_f32_e32 v10, v13, v11
	v_cvt_pk_bf16_f32 v10, v10, v165
	s_nop 0
	global_store_short v[0:1], v10, off offset:1600
	v_cndmask_b32_e64 v10, v112, v68, s[12:13]
	v_cndmask_b32_e64 v13, v113, v69, s[12:13]
	s_waitcnt lgkmcnt(0)
	v_mul_f32_e32 v12, v3, v63
	v_fmac_f32_e32 v12, v10, v9
	v_cvt_pk_bf16_f32 v10, v12, v165
	s_nop 0
	global_store_short v[0:1], v10, off offset:96
	s_waitcnt lgkmcnt(0)
	v_mul_f32_e32 v10, v6, v64
	v_fmac_f32_e32 v10, v13, v4
	v_cvt_pk_bf16_f32 v10, v10, v165
	s_nop 0
	v_cndmask_b32_e64 v13, v114, v70, s[12:13]
	global_store_short v[0:1], v10, off offset:608
	s_waitcnt lgkmcnt(0)
	v_mul_f32_e32 v10, v7, v65
	v_fmac_f32_e32 v10, v13, v5
	v_cvt_pk_bf16_f32 v10, v10, v165
	s_nop 0
	v_cndmask_b32_e64 v13, v115, v71, s[12:13]
	global_store_short v[0:1], v10, off offset:1120
	s_waitcnt lgkmcnt(0)
	v_mul_f32_e32 v10, v2, v66
	v_fmac_f32_e32 v10, v13, v11
	v_cvt_pk_bf16_f32 v10, v10, v165
	s_nop 0
	global_store_short v[0:1], v10, off offset:1632
	v_cndmask_b32_e64 v10, v104, v48, s[12:13]
	v_cndmask_b32_e64 v13, v105, v49, s[12:13]
	s_waitcnt lgkmcnt(0)
	v_mul_f32_e32 v12, v3, v67
	v_fmac_f32_e32 v12, v10, v9
	v_cvt_pk_bf16_f32 v10, v12, v165
	s_nop 0
	global_store_short v[0:1], v10, off offset:128
	s_waitcnt lgkmcnt(0)
	v_mul_f32_e32 v10, v6, v72
	v_fmac_f32_e32 v10, v13, v4
	v_cvt_pk_bf16_f32 v10, v10, v165
	s_nop 0
	v_cndmask_b32_e64 v13, v106, v50, s[12:13]
	global_store_short v[0:1], v10, off offset:640
	s_waitcnt lgkmcnt(0)
	v_mul_f32_e32 v10, v7, v73
	v_fmac_f32_e32 v10, v13, v5
	v_cvt_pk_bf16_f32 v10, v10, v165
	s_nop 0
	v_cndmask_b32_e64 v13, v107, v51, s[12:13]
	global_store_short v[0:1], v10, off offset:1152
	s_waitcnt lgkmcnt(0)
	v_mul_f32_e32 v10, v2, v74
	v_fmac_f32_e32 v10, v13, v11
	v_cvt_pk_bf16_f32 v10, v10, v165
	s_nop 0
	global_store_short v[0:1], v10, off offset:1664
	v_cndmask_b32_e64 v10, v96, v40, s[12:13]
	v_cndmask_b32_e64 v13, v97, v41, s[12:13]
	s_waitcnt lgkmcnt(0)
	v_mul_f32_e32 v12, v3, v75
	v_fmac_f32_e32 v12, v10, v9
	v_cvt_pk_bf16_f32 v10, v12, v165
	s_nop 0
	global_store_short v[0:1], v10, off offset:160
	s_waitcnt lgkmcnt(0)
	v_mul_f32_e32 v10, v6, v76
	v_fmac_f32_e32 v10, v13, v4
	v_cvt_pk_bf16_f32 v10, v10, v165
	s_nop 0
	v_cndmask_b32_e64 v13, v98, v42, s[12:13]
	global_store_short v[0:1], v10, off offset:672
	s_waitcnt lgkmcnt(0)
	v_mul_f32_e32 v10, v7, v77
	v_fmac_f32_e32 v10, v13, v5
	v_cvt_pk_bf16_f32 v10, v10, v165
	s_nop 0
	v_cndmask_b32_e64 v13, v99, v43, s[12:13]
	global_store_short v[0:1], v10, off offset:1184
	s_waitcnt lgkmcnt(0)
	v_mul_f32_e32 v10, v2, v78
	v_fmac_f32_e32 v10, v13, v11
	v_cvt_pk_bf16_f32 v10, v10, v165
	s_nop 0
	global_store_short v[0:1], v10, off offset:1696
	v_cndmask_b32_e64 v10, v80, v36, s[12:13]
	v_cndmask_b32_e64 v13, v81, v37, s[12:13]
	s_waitcnt lgkmcnt(0)
	v_mul_f32_e32 v12, v3, v79
	v_fmac_f32_e32 v12, v10, v9
	v_cvt_pk_bf16_f32 v10, v12, v165
	s_nop 0
	global_store_short v[0:1], v10, off offset:192
	s_waitcnt lgkmcnt(0)
	v_mul_f32_e32 v10, v6, v128
	v_fmac_f32_e32 v10, v13, v4
	v_cvt_pk_bf16_f32 v10, v10, v165
	s_nop 0
	v_cndmask_b32_e64 v13, v82, v38, s[12:13]
	global_store_short v[0:1], v10, off offset:704
	s_waitcnt lgkmcnt(0)
	v_mul_f32_e32 v10, v7, v129
	v_fmac_f32_e32 v10, v13, v5
	v_cvt_pk_bf16_f32 v10, v10, v165
	s_nop 0
	v_cndmask_b32_e64 v13, v83, v39, s[12:13]
	global_store_short v[0:1], v10, off offset:1216
	s_waitcnt lgkmcnt(0)
	v_mul_f32_e32 v10, v2, v130
	v_fmac_f32_e32 v10, v13, v11
	v_cvt_pk_bf16_f32 v10, v10, v165
	s_nop 0
	global_store_short v[0:1], v10, off offset:1728
	v_cndmask_b32_e64 v10, v44, v32, s[12:13]
	s_waitcnt lgkmcnt(0)
	v_mul_f32_e32 v3, v3, v131
	v_fmac_f32_e32 v3, v10, v9
	v_cvt_pk_bf16_f32 v3, v3, v165
	s_nop 0
	v_cndmask_b32_e64 v10, v45, v33, s[12:13]
	global_store_short v[0:1], v3, off offset:224
	s_waitcnt lgkmcnt(0)
	v_mul_f32_e32 v3, v6, v152
	v_fmac_f32_e32 v3, v10, v4
	v_cvt_pk_bf16_f32 v3, v3, v165
	s_nop 0
	v_cndmask_b32_e64 v6, v46, v34, s[12:13]
	global_store_short v[0:1], v3, off offset:736
	s_waitcnt lgkmcnt(0)
	v_mul_f32_e32 v3, v7, v153
	v_fmac_f32_e32 v3, v6, v5
	v_cvt_pk_bf16_f32 v3, v3, v165
	s_nop 0
	v_cndmask_b32_e64 v5, v47, v35, s[12:13]
	s_xor_b64 s[12:13], exec, -1
	global_store_short v[0:1], v3, off offset:1248
	s_waitcnt lgkmcnt(0)
	v_mul_f32_e32 v2, v2, v154
	v_fmac_f32_e32 v2, v5, v11
	v_cvt_pk_bf16_f32 v2, v2, v165
	global_store_short v[0:1], v2, off offset:1760
	s_branch .Lq_next
